# stack19: stack18 + P4 g3 units moved off the critical workgroups 0..127 (they keep sample-NSA + cmp), 8 units each on workgroups 128..255
# baseline (speedup 1.0000x reference)
.LBB0_1268:
	v_readlane_b32 s2, v247, 0
	v_readlane_b32 s3, v247, 1
	s_cmp_lt_i32 s2, 5
	s_cselect_b64 s[2:3], -1, 0
	s_and_b64 s[0:1], s[2:3], s[0:1]
	s_andn2_b64 vcc, exec, s[0:1]
	v_readlane_b32 s0, v248, 60
	v_readlane_b32 s1, v248, 61
	s_nop 1
	v_cndmask_b32_e64 v1, 0, 1, s[0:1]
	v_cmp_ne_u32_e64 s[0:1], 1, v1
	s_nop 1
	v_writelane_b32 v246, s0, 26
	s_nop 1
	v_writelane_b32 v246, s1, 27
	s_mov_b32 s0, s94
	v_writelane_b32 v247, s0, 42
	s_nop 1
	v_writelane_b32 v247, s1, 43
	s_cbranch_vccnz .LBB0_1777
	v_readlane_b32 s0, v246, 26
	v_readlane_b32 s1, v246, 27
	s_movk_i32 s33, 0x400
	s_and_b64 vcc, exec, s[0:1]
	s_mov_b32 s2, s96
	s_cbranch_vccnz .LBB0_1274
	s_cmpk_gt_i32 s96, 0x7f
	s_cbranch_scc0 .LBB0_1272
	s_mul_i32 s0, s96, 8
	s_add_i32 s2, s0, 0xfffffc00
	s_add_i32 s33, s0, 0xfffffc08
	s_cbranch_execz .LBB0_1273
	s_branch .LBB0_1274
.LBB0_1272:
.LBB0_1273:
	s_mul_i32 s2, s96, 0
	s_add_i32 s33, s2, 0
